# windowed attention (latent units): one static s_setprio 1 for waves 4-7, reset to 0 before the hyena sub-phase
# baseline (speedup 1.0000x reference)
; __device__ __forceinline__ int mytid() { int t = threadIdx.x; asm volatile("" : "+v"(t)); return t; }
; #define TILE_LOAD(i, kr, vr) do { if ((i) < ntl) { const int ks0_ = qb * 128 - 128 + 64 * (i); kr = *(const u32x4*)(Kb_lat + (size_t)(ks0_ + lrow) * 256); vr = *(const u32x4*)(Vb + ks0_); } \
;         else { const int c0_ = 64 * ((i) - ntl); kr = *(const u32x4*)(Kb_ctx + (size_t)(c0_ + lrow) * 256); vr = *(const u32x4*)(Vb + SEQ + c0_); } } while (0)
; __device__ __forceinline__ void attn_unit(LAS unsigned char* lds, bf16_t* Y, const bf16_t* KB, const bf16_t* VT, const float* sink, int b, int kvh, int qb, bool isctx) {
;     const int tid = mytid(), lane = tid & 63, wave = __builtin_amdgcn_readfirstlane(tid >> 6), r32 = lane & 31, hi = lane >> 5;
;     const int h = kvh * 4 + (wave >> 1), tq0 = qb * 128 + (wave & 1) * 64;
;     const size_t qrow0 = isctx ? (size_t)RL + b * CTXL + tq0 : (size_t)b * SEQ + tq0;
;     bf16x8 qf[2][4];
; #pragma unroll
;     for (int j = 0; j < 2; ++j)
; #pragma unroll
;         for (int ks = 0; ks < 4; ++ks) qf[j][ks] = *(const bf16x8*)(Y + (qrow0 + 32 * j + r32) * DM + h * 64 + 16 * ks + 8 * hi);
;     const float sk = sink[h] * LOG2E;
;     float mx_[2] = {sk, sk}, l_[2]; l_[0] = l_[1] = (hi == 0) ? 1.f : 0.f;
;     f32x16 o[2][2];
; #pragma unroll
;     for (int j = 0; j < 2; ++j)
; #pragma unroll
;         for (int d = 0; d < 2; ++d) o[j][d] = f32x16{};
;     const int ntl = isctx ? 0 : 6, NT = ntl + 4;
;     const int lrow = tid >> 3, lch = tid & 7;
;     const bf16_t* Kb_lat = KB + ((size_t)b * SEQ) * 256 + kvh * 64 + lch * 8; const bf16_t* Kb_ctx = KB + ((size_t)RL + b * CTXL) * 256 + kvh * 64 + lch * 8;
;     const bf16_t* Vb = VT + (size_t)((b * 4 + kvh) * 64 + lrow) * (SEQ + CTXL) + lch * 8;
;     ...
;     int it = 0; while (!TILE_VALID(it)) ++it;
;     u32x4 kreg, vreg; TILE_LOAD(it, kreg, vreg);
.LBB0_242:
	s_and_b64 vcc, exec, s[34:35]
	s_cbranch_vccz .LBB0_222
	v_readfirstlane_b32 s98, v242
	s_nop 0
	s_cmp_ge_u32 s98, 0x100
	s_cbranch_scc0 .Lattn_prio_skip
	s_setprio 1
.Lattn_prio_skip:
	s_load_dwordx2 s[34:35], s[0:1], 0x58
	s_and_b32 s18, s60, 15
	s_lshl_b32 s61, s18, 7
	s_lshl_b64 s[42:43], s[30:31], 2
	v_mov_b32_e32 v2, v242
	s_waitcnt lgkmcnt(0)
	s_add_u32 s18, s34, s42
	s_addc_u32 s50, s35, s43
	s_bfe_u32 s51, s55, 0x20004
	s_lshl_b32 s35, s51, 2
	v_readfirstlane_b32 s34, v2
	s_ashr_i32 s43, s34, 7
	s_ashr_i32 s42, s55, 6
	s_add_i32 s44, s43, s35
	s_lshl_b32 s35, s55, 7
	s_and_b32 s48, s35, 0x780
	s_and_b32 s34, s34, 64
	s_ashr_i32 s43, s42, 31
	s_or_b32 s49, s34, s48
	s_lshl_b64 s[34:35], s[42:43], 11
	v_and_b32_e32 v3, 31, v2
	s_or_b32 s34, s34, s49
	v_or_b32_e32 v4, s34, v3
	s_lshl_b32 s34, s44, 6
	s_lshl_b32 s46, s42, 8
	v_mov_b32_e32 v5, s35
	s_ashr_i32 s35, s34, 31
	s_ashr_i32 s47, s46, 31
	s_lshl_b64 s[34:35], s[34:35], 1
	s_add_u32 s34, s28, s34
	s_addc_u32 s35, s29, s35
	s_ashr_i32 s45, s44, 31
	v_bfe_u32 v1, v2, 5, 1
	s_lshl_b64 s[44:45], s[44:45], 2
	v_lshlrev_b32_e32 v142, 4, v1
	v_mov_b32_e32 v143, v209
	s_add_u32 s44, s18, s44
	v_lshl_add_u64 v[6:7], s[34:35], 0, v[142:143]
	v_lshlrev_b64 v[138:139], 12, v[4:5]
	s_addc_u32 s45, s50, s45
	s_lshl_b64 s[42:43], s[42:43], 20
	v_lshl_add_u64 v[4:5], v[6:7], 0, v[138:139]
	v_or_b32_e32 v136, 0x20000, v138
	v_mov_b32_e32 v137, v139
	s_add_u32 s42, s40, s42
	global_load_dwordx4 v[96:99], v[4:5], off
	global_load_dwordx4 v[100:103], v[4:5], off offset:32
	global_load_dwordx4 v[104:107], v[4:5], off offset:64
	global_load_dwordx4 v[108:111], v[4:5], off offset:96
	v_lshl_add_u64 v[4:5], v[6:7], 0, v[136:137]
	v_ashrrev_i32_e32 v141, 3, v2
	s_addc_u32 s43, s41, s43
	s_lshl_b32 s50, s51, 6
	s_lshl_b32 s18, s51, 7
	v_lshlrev_b32_e32 v2, 3, v2
	global_load_dwordx4 v[112:115], v[4:5], off
	global_load_dwordx4 v[116:119], v[4:5], off offset:32
	global_load_dwordx4 v[120:123], v[4:5], off offset:64
	global_load_dwordx4 v[124:127], v[4:5], off offset:96
	global_load_dword v0, v209, s[44:45]
	s_add_u32 s44, s42, s18
	v_and_b32_e32 v2, 56, v2
	s_addc_u32 s45, s43, 0
	v_lshlrev_b32_e32 v208, 1, v2
	v_lshl_add_u64 v[4:5], s[44:45], 0, v[208:209]
	s_lshl_b64 s[44:45], s[46:47], 9
	s_add_u32 s18, s40, s44
	s_addc_u32 s45, s41, s45
	s_add_u32 s44, s18, 0x1000000
	s_addc_u32 s45, s45, 0
	s_or_b32 s18, s50, s46
	v_add_u32_e32 v8, s18, v141
	v_mov_b64_e32 v[6:7], s[16:17]
	s_movk_i32 s18, 0x1200
	v_mad_i64_i32 v[6:7], s[46:47], v8, s18, v[6:7]
	s_add_i32 s18, s48, 0xffffff80
	s_sub_i32 s46, s48, 64
	s_cmpk_gt_u32 s46, 0x7ff
	s_cselect_b32 s47, 2, 1
	s_cselect_b32 s46, s48, s46
	s_cmpk_gt_u32 s18, 0x7ff
	s_cselect_b32 s18, s46, s18
	s_waitcnt vmcnt(0)
	v_lshl_add_u64 v[144:145], v[6:7], 0, v[208:209]
	v_add_u32_e32 v6, s18, v141
	v_ashrrev_i32_e32 v7, 31, v6
	v_lshlrev_b64 v[6:7], 9, v[6:7]
	v_lshl_add_u64 v[4:5], v[4:5], 0, v[6:7]
	v_lshl_add_u64 v[6:7], s[18:19], 1, v[144:145]
	global_load_dwordx4 v[132:135], v[6:7], off
	global_load_dwordx4 v[128:131], v[4:5], off
	s_movk_i32 s18, 0x48
	v_mul_lo_u32 v4, v141, s18
	v_and_b32_e32 v5, 64, v243
	v_cmp_eq_u32_e32 vcc, 0, v1
	v_add_lshl_u32 v151, v4, v2, 1
	v_xor_b32_e32 v4, 32, v243
	v_add_u32_e32 v5, 64, v5
	v_cndmask_b32_e64 v143, 0, 1.0, vcc
	v_cmp_lt_i32_e32 vcc, v4, v5
	v_mul_u32_u24_e32 v153, 0x90, v3
	v_lshlrev_b32_e32 v140, 3, v1
	v_cndmask_b32_e32 v4, v243, v4, vcc
	v_lshlrev_b32_e32 v149, 2, v4
	v_or_b32_e32 v4, s49, v3
	v_not_b32_e32 v3, 16
	v_mad_i32_i24 v162, v1, -4, v3
	v_not_b32_e32 v3, 17
	v_mad_i32_i24 v163, v1, -4, v3
	v_not_b32_e32 v3, 18
	v_mad_i32_i24 v164, v1, -4, v3
	v_not_b32_e32 v3, 23
	v_mad_i32_i24 v165, v1, -4, v3
	v_not_b32_e32 v3, 24
	v_mad_i32_i24 v166, v1, -4, v3
	v_not_b32_e32 v3, 25
	v_mad_i32_i24 v167, v1, -4, v3
	v_not_b32_e32 v3, 26
	s_cselect_b32 s66, s47, 0
	s_mov_b64 s[46:47], 0x1000
	v_mul_i32_i24_e32 v152, -4, v1
	v_mad_i32_i24 v154, v1, -4, -1
	v_mad_i32_i24 v155, v1, -4, -2
	v_mad_i32_i24 v156, v1, -4, -3
	v_mad_i32_i24 v157, v1, -4, -8
	v_mad_i32_i24 v158, v1, -4, -9
	v_mad_i32_i24 v159, v1, -4, -10
	v_mad_i32_i24 v160, v1, -4, -11
	v_mad_i32_i24 v161, v1, -4, -16
	v_mad_i32_i24 v168, v1, -4, v3
	v_subrev_u32_e32 v1, s48, v4
	s_mov_b32 s60, 0
	v_lshl_add_u64 v[146:147], v[144:145], 0, s[46:47]
	v_add_u32_e32 v169, -1, v1
	v_subrev_u32_e32 v170, 33, v1
	v_add_u32_e32 v171, 31, v1
	s_addk_i32 s61, 0xff80
	s_lshl_b32 s62, s50, 1
	v_lshlrev_b32_e32 v208, 1, v2
	v_mov_b32_e32 v172, v143
	s_waitcnt vmcnt(0)
	v_mul_f32_e32 v150, 0x3fb8aa3b, v0
	v_mov_b32_e32 v0, 0
	v_mov_b32_e32 v148, v150
	v_mov_b32_e32 v1, v0
	v_mov_b32_e32 v2, v0
	v_mov_b32_e32 v3, v0
	v_mov_b32_e32 v4, v0
	v_mov_b32_e32 v5, v0
	v_mov_b32_e32 v6, v0
	v_mov_b32_e32 v7, v0
	v_mov_b32_e32 v8, v0
	v_mov_b32_e32 v9, v0
	v_mov_b32_e32 v10, v0
	v_mov_b32_e32 v11, v0
	v_mov_b32_e32 v12, v0
	v_mov_b32_e32 v13, v0
	v_mov_b32_e32 v14, v0
	v_mov_b32_e32 v15, v0
	v_mov_b32_e32 v16, v0
	v_mov_b32_e32 v17, v0
	v_mov_b32_e32 v18, v0
	v_mov_b32_e32 v19, v0
	v_mov_b32_e32 v20, v0
	v_mov_b32_e32 v21, v0
	v_mov_b32_e32 v22, v0
	v_mov_b32_e32 v23, v0
	v_mov_b32_e32 v24, v0
	v_mov_b32_e32 v25, v0
	v_mov_b32_e32 v26, v0
	v_mov_b32_e32 v27, v0
	v_mov_b32_e32 v28, v0
	v_mov_b32_e32 v29, v0
	v_mov_b32_e32 v30, v0
	v_mov_b32_e32 v31, v0
	v_mov_b32_e32 v32, v0
	v_mov_b32_e32 v33, v0
	v_mov_b32_e32 v34, v0
	v_mov_b32_e32 v35, v0
	v_mov_b32_e32 v36, v0
	v_mov_b32_e32 v37, v0
	v_mov_b32_e32 v38, v0
	v_mov_b32_e32 v39, v0
	v_mov_b32_e32 v40, v0
	v_mov_b32_e32 v41, v0
	v_mov_b32_e32 v42, v0
	v_mov_b32_e32 v43, v0
	v_mov_b32_e32 v44, v0
	v_mov_b32_e32 v45, v0
	v_mov_b32_e32 v46, v0
	v_mov_b32_e32 v47, v0
	v_mov_b32_e32 v48, v0
	v_mov_b32_e32 v49, v0
	v_mov_b32_e32 v50, v0
	v_mov_b32_e32 v51, v0
	v_mov_b32_e32 v52, v0
	v_mov_b32_e32 v53, v0
	v_mov_b32_e32 v54, v0
	v_mov_b32_e32 v55, v0
	v_mov_b32_e32 v56, v0
	v_mov_b32_e32 v57, v0
	v_mov_b32_e32 v58, v0
	v_mov_b32_e32 v59, v0
	v_mov_b32_e32 v60, v0
	v_mov_b32_e32 v61, v0
	v_mov_b32_e32 v62, v0
	v_mov_b32_e32 v63, v0

; #define LAS __attribute__((address_space(3)))
; __device__ __forceinline__ void hyena_units(CArgsP a, int l, LAS unsigned char* lds) {
;     for (int c = blockIdx.x; c < 512; c += gridDim.x) {
;         hyena_chan<2048>(a, l, lds, c, 0, (const bf16_t*)(a->ws + WS_KREVL) + (size_t)c * 4096, (const bf16_t*)(a->ws + WS_KREVL) + (size_t)(512 + c) * 4096);
;         if (l == 0) hyena_chan<256>(a, l, lds, c, RL, (const bf16_t*)(a->ws + WS_KREVC) + (size_t)c * 512, (const bf16_t*)(a->ws + WS_KREVC) + (size_t)(512 + c) * 512);
.LBB0_260:
	s_setprio 0
	v_readlane_b32 s16, v253, 12
	v_readlane_b32 s17, v253, 13
	s_andn2_b64 vcc, exec, s[16:17]
	s_cbranch_vccnz .LBB0_354
	s_add_u32 s15, s72, 0x300000
	s_addc_u32 s18, s73, 0
	v_writelane_b32 v255, s80, 9
	s_add_u32 s69, s72, 0x1aa00000
	s_addc_u32 s75, s73, 0
	v_writelane_b32 v255, s81, 10
	s_lshl_b32 s74, s14, 10
	v_writelane_b32 v255, s82, 11
	s_add_u32 s2, s72, 0xb00000
	v_readlane_b32 s16, v253, 0
	v_writelane_b32 v255, s83, 12
	s_addc_u32 s28, s73, 0
	s_mov_b32 s30, s16
	s_branch .LBB0_263
